# pipelined attention v10: next-tile K loads stay in the MFMA block, V loads issued at the start of the softmax block
# baseline (speedup 1.0000x reference)
.Lpipe_nost_p:
	s_add_i32 s14, s12, 0x43
	s_cmp_ge_i32 s14, s6
	s_cbranch_scc1 .Lpipe_nopfk_p
	v_add_co_u32_e32 v184, vcc, 0x10000, v144
	global_load_dwordx4 v[116:119], v[144:145], off
	s_nop 0
	v_addc_co_u32_e32 v185, vcc, 0, v145, vcc
	global_load_dwordx4 v[120:123], v[184:185], off
	v_lshl_add_u64 v[144:145], v[144:145], 0, s[90:91]

; DI void attn_s(const unsigned char* sK, int tt, int qb, int qs, int sub, int l31, int h,
;                const bf16x8 (&qf)[4], f32x16 (&O)[4], float& m, float& l, bf16x8 (&pb)[4]) {
;     ...
;     } else if (tt >= 2 * qb + 1) {
;         const int kbase = (tt - 1) * 64 + 4 * h;
; #pragma unroll
;         for (int k2 = 0; k2 < 2; ++k2)
; #pragma unroll
;             for (int i = 0; i < 16; ++i) {
;                 const int key = kbase + k2 * 32 + (i & 3) + 8 * (i >> 2);
;                 if (key > qs) st[k2][i] = -INFINITY;
;             }
;     }
.Lpipe_loop:
	v_add3_u32 v191, s98, v156, v98
	ds_read_b128 v[172:175], v191 offset:17408
	ds_read_b128 v[176:179], v191 offset:22016
	ds_read_b128 v[180:183], v191 offset:26624
	ds_read_b128 v[192:195], v191 offset:31232
	ds_read_b128 v[200:203], v191 offset:17440
	ds_read_b128 v[204:207], v191 offset:22048
	ds_read_b128 v[208:211], v191 offset:26656
	ds_read_b128 v[212:215], v191 offset:31264
	s_add_i32 s14, s12, 0x43
	s_cmp_ge_i32 s14, s6
	s_cbranch_scc1 .Lpipe_nopfv_l
	global_load_dwordx4 v[124:127], v[142:143], off
	v_add_co_u32_e32 v184, vcc, 0x80000, v142
	s_nop 1
	v_addc_co_u32_e32 v185, vcc, 0, v143, vcc
	global_load_dwordx4 v[128:131], v[184:185], off
	v_lshl_add_u64 v[142:143], v[142:143], 0, s[88:89]
.Lpipe_nopfv_l:
	s_add_i32 s14, s12, 0x41
	s_cmp_le_i32 s14, s0
	s_cbranch_scc1 .Lpipe_nomask_l
	v_subrev_u32_e32 v159, 59, v158
	v_cmp_gt_i32_e32 vcc, v159, v138
	s_nop 1
	v_cndmask_b32_e32 v160, v82, v188, vcc
	v_cmp_lt_i32_e32 vcc, v159, v138
	v_subrev_u32_e32 v159, 57, v158
	s_nop 0
	v_cndmask_b32_e32 v82, v160, v82, vcc
	v_cndmask_b32_e32 v83, v188, v83, vcc
	v_cmp_le_i32_e32 vcc, v159, v138
	v_subrev_u32_e32 v159, 56, v158
	s_nop 0
	v_cndmask_b32_e32 v84, v188, v84, vcc
	v_cmp_le_i32_e32 vcc, v159, v138
	v_subrev_u32_e32 v159, 51, v158
	s_nop 0
	v_cndmask_b32_e32 v85, v188, v85, vcc
	v_cmp_le_i32_e32 vcc, v159, v138
	v_subrev_u32_e32 v159, 50, v158
	s_nop 0
	v_cndmask_b32_e32 v86, v188, v86, vcc
	v_cmp_le_i32_e32 vcc, v159, v138
	v_subrev_u32_e32 v159, 49, v158
	s_nop 0
	v_cndmask_b32_e32 v87, v188, v87, vcc
	v_cmp_le_i32_e32 vcc, v159, v138
	v_subrev_u32_e32 v159, 48, v158
	s_nop 0
	v_cndmask_b32_e32 v88, v188, v88, vcc
	v_cmp_le_i32_e32 vcc, v159, v138
	v_subrev_u32_e32 v159, 43, v158
	s_nop 0
	v_cndmask_b32_e32 v89, v188, v89, vcc
	v_cmp_le_i32_e32 vcc, v159, v138
	v_subrev_u32_e32 v159, 42, v158
	s_nop 0
	v_cndmask_b32_e32 v90, v188, v90, vcc
	v_cmp_le_i32_e32 vcc, v159, v138
	v_subrev_u32_e32 v159, 41, v158
	s_nop 0
	v_cndmask_b32_e32 v91, v188, v91, vcc
	v_cmp_le_i32_e32 vcc, v159, v138
	v_subrev_u32_e32 v159, 40, v158
	s_nop 0
	v_cndmask_b32_e32 v92, v188, v92, vcc
	v_cmp_le_i32_e32 vcc, v159, v138
	v_subrev_u32_e32 v159, 35, v158
	s_nop 0
	v_cndmask_b32_e32 v93, v188, v93, vcc
	v_cmp_le_i32_e32 vcc, v159, v138
	v_subrev_u32_e32 v159, 34, v158
	s_nop 0
	v_cndmask_b32_e32 v94, v188, v94, vcc
	v_cmp_le_i32_e32 vcc, v159, v138
	v_subrev_u32_e32 v159, 33, v158
	s_nop 0
	v_cndmask_b32_e32 v95, v188, v95, vcc
	v_cmp_le_i32_e32 vcc, v159, v138
	v_subrev_u32_e32 v159, 32, v158
	s_nop 0
	v_cndmask_b32_e32 v96, v188, v96, vcc
	v_cmp_le_i32_e32 vcc, v159, v138
	v_subrev_u32_e32 v159, 27, v158
	s_nop 0
	v_cndmask_b32_e32 v97, v188, v97, vcc
	v_cmp_le_i32_e32 vcc, v159, v138
	v_subrev_u32_e32 v159, 26, v158
	s_nop 0
	v_cndmask_b32_e32 v66, v188, v66, vcc
	v_cmp_le_i32_e32 vcc, v159, v138
	v_subrev_u32_e32 v159, 25, v158
	s_nop 0
	v_cndmask_b32_e32 v67, v188, v67, vcc
	v_cmp_le_i32_e32 vcc, v159, v138
	v_subrev_u32_e32 v159, 24, v158
	s_nop 0
	v_cndmask_b32_e32 v68, v188, v68, vcc
	v_cmp_le_i32_e32 vcc, v159, v138
	v_subrev_u32_e32 v159, 19, v158
	s_nop 0
	v_cndmask_b32_e32 v69, v188, v69, vcc
	v_cmp_le_i32_e32 vcc, v159, v138
	v_subrev_u32_e32 v159, 18, v158
	s_nop 0
	v_cndmask_b32_e32 v70, v188, v70, vcc
	v_cmp_le_i32_e32 vcc, v159, v138
	v_subrev_u32_e32 v159, 17, v158
	s_nop 0
	v_cndmask_b32_e32 v71, v188, v71, vcc
	v_cmp_le_i32_e32 vcc, v159, v138
	v_add_u32_e32 v159, -16, v158
	s_nop 0
	v_cndmask_b32_e32 v72, v188, v72, vcc
	v_cmp_le_i32_e32 vcc, v159, v138
	v_add_u32_e32 v159, -11, v158
	s_nop 0
	v_cndmask_b32_e32 v73, v188, v73, vcc
	v_cmp_le_i32_e32 vcc, v159, v138
	v_add_u32_e32 v159, -10, v158
	s_nop 0
	v_cndmask_b32_e32 v74, v188, v74, vcc
	v_cmp_le_i32_e32 vcc, v159, v138
	v_add_u32_e32 v159, -9, v158
	s_nop 0
	v_cndmask_b32_e32 v75, v188, v75, vcc
	v_cmp_le_i32_e32 vcc, v159, v138
	v_add_u32_e32 v159, -8, v158
	s_nop 0
	v_cndmask_b32_e32 v76, v188, v76, vcc
	v_cmp_le_i32_e32 vcc, v159, v138
	v_add_u32_e32 v159, -3, v158
	s_nop 0
	v_cndmask_b32_e32 v77, v188, v77, vcc
	v_cmp_le_i32_e32 vcc, v159, v138
	v_add_u32_e32 v159, -2, v158
	s_nop 0
	v_cndmask_b32_e32 v78, v188, v78, vcc
	v_cmp_le_i32_e32 vcc, v159, v138
	v_add_u32_e32 v159, -1, v158
	s_nop 0
	v_cndmask_b32_e32 v79, v188, v79, vcc
	v_cmp_le_i32_e32 vcc, v159, v138
	s_nop 1
	v_cndmask_b32_e32 v80, v188, v80, vcc
	v_cmp_le_i32_e32 vcc, v158, v138
	s_nop 1
	v_cndmask_b32_e32 v81, v188, v81, vcc
